# FF1 GEMM K-loop re-scheduled: 2 LDS stages, one barrier per K-step, LDS writes/reads and next-tile loads interleaved with MFMAs
# speedup vs baseline: 1.0155x; 1.0155x over previous
; #define MFMA(a, b, c) __builtin_amdgcn_mfma_f32_32x32x16_f16(__builtin_bit_cast(h16x8, (a)), __builtin_bit_cast(h16x8, (b)), (c), 0, 0, 0)
; template <int MODE, bool BIG = false> DI void gemm_tile(const Params& p, int tm, int tn, int kv, char* smem) {
;     ...
;     char* Bs2 = smem + 256 * 80;
;     uint4 ra[4], rb[2];
; #pragma unroll
;     for (int i = 0; i < 4; ++i) { const int id = tid + 256 * i; ra[i] = load_a<MODE>(p, tma, kv, id >> 2, 0, id & 3); }
; #pragma unroll
;     for (int i = 0; i < 2; ++i) { const int id = tid + 256 * i; rb[i] = load_b<MODE>(p, tn, kv, id >> 2, 0, id & 3); }
;     for (int kt = 0; kt < 2 * KT; ++kt) {
;       __syncthreads();
; #pragma unroll
;       for (int i = 0; i < 4; ++i) { const int id = tid + 256 * i; *(uint4*)(As + (id >> 2) * 80 + (id & 3) * 16) = ra[i]; }
; #pragma unroll
;       for (int i = 0; i < 2; ++i) { const int id = tid + 256 * i; *(uint4*)(Bs2 + (id >> 2) * 80 + (id & 3) * 16) = rb[i]; }
;       __syncthreads();
;       if (kt + 1 < 2 * KT) {
;         const int k1 = kt + 1;
; #pragma unroll
;         for (int i = 0; i < 4; ++i) { const int id = tid + 256 * i; ra[i] = load_a<MODE>(p, tma, kv, id >> 2, k1 >> 1, ((k1 & 1) << 2) | (id & 3)); }
; #pragma unroll
;         for (int i = 0; i < 2; ++i) { const int id = tid + 256 * i; rb[i] = load_b<MODE>(p, tn, kv, id >> 2, k1 >> 1, ((k1 & 1) << 2) | (id & 3)); }
;       }
;       {
;         bf16x8 af[2][4], bfr[2][2];
; #pragma unroll
;         for (int s = 0; s < 2; ++s) {
; #pragma unroll
;           for (int i = 0; i < 4; ++i) af[s][i] = *(const bf16x8*)(As + (wm * 128 + i * 32 + r) * 80 + s * 32 + hf * 16);
; #pragma unroll
;           for (int j = 0; j < 2; ++j) bfr[s][j] = *(const bf16x8*)(Bs2 + (wn * 64 + j * 32 + r) * 80 + s * 32 + hf * 16);
;         }
;         __builtin_amdgcn_s_setprio(1);
; #pragma unroll
;         for (int s = 0; s < 2; ++s)
; #pragma unroll
;           for (int i = 0; i < 4; ++i)
; #pragma unroll
;             for (int j = 0; j < 2; ++j) acc[i][j] = MFMA(af[s][i], bfr[s][j], acc[i][j]);
;         __builtin_amdgcn_s_setprio(0);
;       }
;     }
.LBB0_978:
	s_barrier
	s_waitcnt vmcnt(5)
	ds_write_b128 v175, v[132:135]
	s_waitcnt vmcnt(4)
	ds_write_b128 v174, v[128:131]
	s_waitcnt vmcnt(3)
	ds_write_b128 v177, v[140:143]
	s_waitcnt vmcnt(2)
	ds_write_b128 v176, v[136:139]
	s_waitcnt vmcnt(1)
	ds_write_b128 v175, v[148:151] offset:20480
	s_waitcnt vmcnt(0)
	ds_write_b128 v174, v[144:147] offset:20480
	s_and_b32 s15, s7, 0x7c0
	s_lshl_b32 s15, s15, 1
	v_and_or_b32 v128, s6, 4, v178
	s_add_u32 s16, s22, s15
	v_lshlrev_b32_e32 v152, 4, v128
	s_addc_u32 s17, s23, 0
	v_lshl_add_u64 v[128:129], s[16:17], 0, v[152:153]
	s_add_u32 s16, s0, s15
	v_lshl_add_u64 v[130:131], v[128:129], 0, v[154:155]
	v_lshl_add_u64 v[136:137], v[128:129], 0, v[156:157]
	v_lshl_add_u64 v[138:139], v[128:129], 0, v[158:159]
	v_lshl_add_u64 v[144:145], v[128:129], 0, v[160:161]
	s_addc_u32 s17, s1, 0
	global_load_dwordx4 v[132:135], v[130:131], off
	s_nop 0
	global_load_dwordx4 v[128:131], v[136:137], off
	global_load_dwordx4 v[140:143], v[138:139], off
	s_nop 0
	global_load_dwordx4 v[136:139], v[144:145], off
	v_lshl_add_u64 v[144:145], s[16:17], 0, v[152:153]
	v_lshl_add_u64 v[146:147], v[144:145], 0, v[162:163]
	v_lshl_add_u64 v[144:145], v[144:145], 0, v[164:165]
	global_load_dwordx4 v[148:151], v[146:147], off
	s_nop 0
	global_load_dwordx4 v[144:147], v[144:145], off
	s_add_i32 s6, s6, 4
	s_add_i32 s7, s7, 32
	s_waitcnt lgkmcnt(0)
	s_barrier
	ds_read_b128 v[180:183], v170
	ds_read_b128 v[188:191], v170 offset:2560
	ds_read_b128 v[196:199], v170 offset:5120
	ds_read_b128 v[204:207], v172
	ds_read_b128 v[212:215], v171 offset:20480
	ds_read_b128 v[220:223], v171 offset:23040
.Lgk_ff1_loop:
	ds_read_b128 v[184:187], v170 offset:32
	ds_read_b128 v[192:195], v170 offset:2592
	ds_read_b128 v[200:203], v170 offset:5152
	ds_read_b128 v[208:211], v172 offset:32
	ds_read_b128 v[216:219], v171 offset:20512
	ds_read_b128 v[224:227], v171 offset:23072
	s_setprio 1
	s_waitcnt lgkmcnt(6)
	v_mfma_f32_32x32x16_f16 v[112:127], v[180:183], v[212:215], v[112:127]
	s_waitcnt vmcnt(5)
	ds_write_b128 v175, v[132:135] offset:32768
	v_mfma_f32_32x32x16_f16 v[96:111], v[180:183], v[220:223], v[96:111]
	s_waitcnt vmcnt(4)
	ds_write_b128 v174, v[128:131] offset:32768
	v_mfma_f32_32x32x16_f16 v[80:95], v[188:191], v[212:215], v[80:95]
	s_waitcnt vmcnt(3)
	ds_write_b128 v177, v[140:143] offset:32768
	v_mfma_f32_32x32x16_f16 v[64:79], v[188:191], v[220:223], v[64:79]
	s_waitcnt vmcnt(2)
	ds_write_b128 v176, v[136:139] offset:32768
	v_mfma_f32_32x32x16_f16 v[48:63], v[196:199], v[212:215], v[48:63]
	s_waitcnt vmcnt(1)
	ds_write_b128 v175, v[148:151] offset:53248
	v_mfma_f32_32x32x16_f16 v[32:47], v[196:199], v[220:223], v[32:47]
	s_waitcnt vmcnt(0)
	ds_write_b128 v174, v[144:147] offset:53248
	v_mfma_f32_32x32x16_f16 v[16:31], v[204:207], v[212:215], v[16:31]
	s_and_b32 s15, s7, 0x7c0
	s_lshl_b32 s15, s15, 1
	v_and_or_b32 v128, s6, 4, v178
	s_add_u32 s16, s22, s15
	v_lshlrev_b32_e32 v152, 4, v128
	s_addc_u32 s17, s23, 0
	v_lshl_add_u64 v[128:129], s[16:17], 0, v[152:153]
	s_add_u32 s16, s0, s15
	v_lshl_add_u64 v[130:131], v[128:129], 0, v[154:155]
	v_lshl_add_u64 v[136:137], v[128:129], 0, v[156:157]
	v_mfma_f32_32x32x16_f16 v[0:15], v[204:207], v[220:223], v[0:15]
	v_lshl_add_u64 v[138:139], v[128:129], 0, v[158:159]
	v_lshl_add_u64 v[144:145], v[128:129], 0, v[160:161]
	s_addc_u32 s17, s1, 0
	global_load_dwordx4 v[132:135], v[130:131], off
	s_nop 0
	global_load_dwordx4 v[128:131], v[136:137], off
	global_load_dwordx4 v[140:143], v[138:139], off
	s_nop 0
	global_load_dwordx4 v[136:139], v[144:145], off
	v_lshl_add_u64 v[144:145], s[16:17], 0, v[152:153]
	v_lshl_add_u64 v[146:147], v[144:145], 0, v[162:163]
	v_lshl_add_u64 v[144:145], v[144:145], 0, v[164:165]
	global_load_dwordx4 v[148:151], v[146:147], off
	s_nop 0
	global_load_dwordx4 v[144:147], v[144:145], off
	s_add_i32 s6, s6, 4
	s_add_i32 s7, s7, 32
	s_waitcnt lgkmcnt(0)
	s_barrier
	ds_read_b128 v[180:183], v170 offset:32768
	ds_read_b128 v[188:191], v170 offset:35328
	ds_read_b128 v[196:199], v170 offset:37888
	ds_read_b128 v[204:207], v172 offset:32768
	ds_read_b128 v[212:215], v171 offset:53248
	ds_read_b128 v[220:223], v171 offset:55808
	v_mfma_f32_32x32x16_f16 v[112:127], v[184:187], v[216:219], v[112:127]
	v_mfma_f32_32x32x16_f16 v[96:111], v[184:187], v[224:227], v[96:111]
	v_mfma_f32_32x32x16_f16 v[80:95], v[192:195], v[216:219], v[80:95]
	v_mfma_f32_32x32x16_f16 v[64:79], v[192:195], v[224:227], v[64:79]
	v_mfma_f32_32x32x16_f16 v[48:63], v[200:203], v[216:219], v[48:63]
	v_mfma_f32_32x32x16_f16 v[32:47], v[200:203], v[224:227], v[32:47]
	v_mfma_f32_32x32x16_f16 v[16:31], v[208:211], v[216:219], v[16:31]
	v_mfma_f32_32x32x16_f16 v[0:15], v[208:211], v[224:227], v[0:15]
	s_setprio 0
	ds_read_b128 v[184:187], v170 offset:32800
	ds_read_b128 v[192:195], v170 offset:35360
	ds_read_b128 v[200:203], v170 offset:37920
	ds_read_b128 v[208:211], v172 offset:32800
	ds_read_b128 v[216:219], v171 offset:53280
	ds_read_b128 v[224:227], v171 offset:55840
	s_setprio 1
	s_waitcnt lgkmcnt(6)
	v_mfma_f32_32x32x16_f16 v[112:127], v[180:183], v[212:215], v[112:127]
	s_waitcnt vmcnt(5)
	ds_write_b128 v175, v[132:135]
	v_mfma_f32_32x32x16_f16 v[96:111], v[180:183], v[220:223], v[96:111]
	s_waitcnt vmcnt(4)
	ds_write_b128 v174, v[128:131]
	v_mfma_f32_32x32x16_f16 v[80:95], v[188:191], v[212:215], v[80:95]
	s_waitcnt vmcnt(3)
	ds_write_b128 v177, v[140:143]
	v_mfma_f32_32x32x16_f16 v[64:79], v[188:191], v[220:223], v[64:79]
	s_waitcnt vmcnt(2)
	ds_write_b128 v176, v[136:139]
	v_mfma_f32_32x32x16_f16 v[48:63], v[196:199], v[212:215], v[48:63]
	s_waitcnt vmcnt(1)
	ds_write_b128 v175, v[148:151] offset:20480
	v_mfma_f32_32x32x16_f16 v[32:47], v[196:199], v[220:223], v[32:47]
	s_waitcnt vmcnt(0)
	ds_write_b128 v174, v[144:147] offset:20480
	v_mfma_f32_32x32x16_f16 v[16:31], v[204:207], v[212:215], v[16:31]
	s_and_b32 s15, s7, 0x7c0
	s_lshl_b32 s15, s15, 1
	v_and_or_b32 v128, s6, 4, v178
	s_add_u32 s16, s22, s15
	v_lshlrev_b32_e32 v152, 4, v128
	s_addc_u32 s17, s23, 0
	v_lshl_add_u64 v[128:129], s[16:17], 0, v[152:153]
	s_add_u32 s16, s0, s15
	v_lshl_add_u64 v[130:131], v[128:129], 0, v[154:155]
	v_lshl_add_u64 v[136:137], v[128:129], 0, v[156:157]
	v_mfma_f32_32x32x16_f16 v[0:15], v[204:207], v[220:223], v[0:15]
	v_lshl_add_u64 v[138:139], v[128:129], 0, v[158:159]
	v_lshl_add_u64 v[144:145], v[128:129], 0, v[160:161]
	s_addc_u32 s17, s1, 0
	global_load_dwordx4 v[132:135], v[130:131], off
	s_nop 0
	global_load_dwordx4 v[128:131], v[136:137], off
	global_load_dwordx4 v[140:143], v[138:139], off
	s_nop 0
	global_load_dwordx4 v[136:139], v[144:145], off
	v_lshl_add_u64 v[144:145], s[16:17], 0, v[152:153]
	v_lshl_add_u64 v[146:147], v[144:145], 0, v[162:163]
	v_lshl_add_u64 v[144:145], v[144:145], 0, v[164:165]
	global_load_dwordx4 v[148:151], v[146:147], off
	s_nop 0
	global_load_dwordx4 v[144:147], v[144:145], off
	s_add_i32 s6, s6, 4
	s_add_i32 s7, s7, 32
	s_waitcnt lgkmcnt(0)
	s_barrier
; #define MFMA(a, b, c) __builtin_amdgcn_mfma_f32_32x32x16_f16(__builtin_bit_cast(h16x8, (a)), __builtin_bit_cast(h16x8, (b)), (c), 0, 0, 0)
; template <int MODE, bool BIG = false> DI void gemm_tile(const Params& p, int tm, int tn, int kv, char* smem) {
;     ...
;     char* Bs2 = smem + 256 * 80;
;     uint4 ra[4], rb[2];
; #pragma unroll
;     for (int i = 0; i < 4; ++i) { const int id = tid + 256 * i; ra[i] = load_a<MODE>(p, tma, kv, id >> 2, 0, id & 3); }
; #pragma unroll
;     for (int i = 0; i < 2; ++i) { const int id = tid + 256 * i; rb[i] = load_b<MODE>(p, tn, kv, id >> 2, 0, id & 3); }
;     for (int kt = 0; kt < 2 * KT; ++kt) {
;       __syncthreads();
; #pragma unroll
;       for (int i = 0; i < 4; ++i) { const int id = tid + 256 * i; *(uint4*)(As + (id >> 2) * 80 + (id & 3) * 16) = ra[i]; }
; #pragma unroll
;       for (int i = 0; i < 2; ++i) { const int id = tid + 256 * i; *(uint4*)(Bs2 + (id >> 2) * 80 + (id & 3) * 16) = rb[i]; }
;       __syncthreads();
;       if (kt + 1 < 2 * KT) {
;         const int k1 = kt + 1;
; #pragma unroll
;         for (int i = 0; i < 4; ++i) { const int id = tid + 256 * i; ra[i] = load_a<MODE>(p, tma, kv, id >> 2, k1 >> 1, ((k1 & 1) << 2) | (id & 3)); }
; #pragma unroll
;         for (int i = 0; i < 2; ++i) { const int id = tid + 256 * i; rb[i] = load_b<MODE>(p, tn, kv, id >> 2, k1 >> 1, ((k1 & 1) << 2) | (id & 3)); }
;       }
;       {
;         bf16x8 af[2][4], bfr[2][2];
; #pragma unroll
;         for (int s = 0; s < 2; ++s) {
; #pragma unroll
;           for (int i = 0; i < 4; ++i) af[s][i] = *(const bf16x8*)(As + (wm * 128 + i * 32 + r) * 80 + s * 32 + hf * 16);
; #pragma unroll
;           for (int j = 0; j < 2; ++j) bfr[s][j] = *(const bf16x8*)(Bs2 + (wn * 64 + j * 32 + r) * 80 + s * 32 + hf * 16);
;         }
;         __builtin_amdgcn_s_setprio(1);
; #pragma unroll
;         for (int s = 0; s < 2; ++s)
; #pragma unroll
;           for (int i = 0; i < 4; ++i)
; #pragma unroll
;             for (int j = 0; j < 2; ++j) acc[i][j] = MFMA(af[s][i], bfr[s][j], acc[i][j]);
;         __builtin_amdgcn_s_setprio(0);
;       }
;     }
	ds_read_b128 v[180:183], v170
	ds_read_b128 v[188:191], v170 offset:2560
	ds_read_b128 v[196:199], v170 offset:5120
	ds_read_b128 v[204:207], v172
	ds_read_b128 v[212:215], v171 offset:20480
	ds_read_b128 v[220:223], v171 offset:23040
	v_mfma_f32_32x32x16_f16 v[112:127], v[184:187], v[216:219], v[112:127]
	v_mfma_f32_32x32x16_f16 v[96:111], v[184:187], v[224:227], v[96:111]
	v_mfma_f32_32x32x16_f16 v[80:95], v[192:195], v[216:219], v[80:95]
	v_mfma_f32_32x32x16_f16 v[64:79], v[192:195], v[224:227], v[64:79]
	v_mfma_f32_32x32x16_f16 v[48:63], v[200:203], v[216:219], v[48:63]
	v_mfma_f32_32x32x16_f16 v[32:47], v[200:203], v[224:227], v[32:47]
	v_mfma_f32_32x32x16_f16 v[16:31], v[208:211], v[216:219], v[16:31]
	v_mfma_f32_32x32x16_f16 v[0:15], v[208:211], v[224:227], v[0:15]
	s_setprio 0
	s_cmpk_eq_i32 s6, 0x80
	s_cbranch_scc0 .Lgk_ff1_loop
	ds_read_b128 v[184:187], v170 offset:32
	ds_read_b128 v[192:195], v170 offset:2592
	ds_read_b128 v[200:203], v170 offset:5152
	ds_read_b128 v[208:211], v172 offset:32
	ds_read_b128 v[216:219], v171 offset:20512
	ds_read_b128 v[224:227], v171 offset:23072
	s_setprio 1
	s_waitcnt lgkmcnt(6)
	v_mfma_f32_32x32x16_f16 v[112:127], v[180:183], v[212:215], v[112:127]
	s_waitcnt vmcnt(5)
	ds_write_b128 v175, v[132:135] offset:32768
	v_mfma_f32_32x32x16_f16 v[96:111], v[180:183], v[220:223], v[96:111]
	s_waitcnt vmcnt(4)
	ds_write_b128 v174, v[128:131] offset:32768
	v_mfma_f32_32x32x16_f16 v[80:95], v[188:191], v[212:215], v[80:95]
	s_waitcnt vmcnt(3)
	ds_write_b128 v177, v[140:143] offset:32768
	v_mfma_f32_32x32x16_f16 v[64:79], v[188:191], v[220:223], v[64:79]
	s_waitcnt vmcnt(2)
	ds_write_b128 v176, v[136:139] offset:32768
	v_mfma_f32_32x32x16_f16 v[48:63], v[196:199], v[212:215], v[48:63]
	s_waitcnt vmcnt(1)
	ds_write_b128 v175, v[148:151] offset:53248
	v_mfma_f32_32x32x16_f16 v[32:47], v[196:199], v[220:223], v[32:47]
	s_waitcnt vmcnt(0)
	ds_write_b128 v174, v[144:147] offset:53248
	v_mfma_f32_32x32x16_f16 v[16:31], v[204:207], v[212:215], v[16:31]
	v_mfma_f32_32x32x16_f16 v[0:15], v[204:207], v[220:223], v[0:15]
	s_waitcnt lgkmcnt(0)
	s_barrier
	ds_read_b128 v[180:183], v170 offset:32768
	ds_read_b128 v[188:191], v170 offset:35328
	ds_read_b128 v[196:199], v170 offset:37888
	ds_read_b128 v[204:207], v172 offset:32768
	ds_read_b128 v[212:215], v171 offset:53248
	ds_read_b128 v[220:223], v171 offset:55808
	v_mfma_f32_32x32x16_f16 v[112:127], v[184:187], v[216:219], v[112:127]
	v_mfma_f32_32x32x16_f16 v[96:111], v[184:187], v[224:227], v[96:111]
	v_mfma_f32_32x32x16_f16 v[80:95], v[192:195], v[216:219], v[80:95]
	v_mfma_f32_32x32x16_f16 v[64:79], v[192:195], v[224:227], v[64:79]
	v_mfma_f32_32x32x16_f16 v[48:63], v[200:203], v[216:219], v[48:63]
	v_mfma_f32_32x32x16_f16 v[32:47], v[200:203], v[224:227], v[32:47]
	v_mfma_f32_32x32x16_f16 v[16:31], v[208:211], v[216:219], v[16:31]
	v_mfma_f32_32x32x16_f16 v[0:15], v[208:211], v[224:227], v[0:15]
	s_setprio 0
	ds_read_b128 v[184:187], v170 offset:32800
	ds_read_b128 v[192:195], v170 offset:35360
	ds_read_b128 v[200:203], v170 offset:37920
	ds_read_b128 v[208:211], v172 offset:32800
	ds_read_b128 v[216:219], v171 offset:53280
	ds_read_b128 v[224:227], v171 offset:55840
	s_setprio 1
	s_waitcnt lgkmcnt(6)
	v_mfma_f32_32x32x16_f16 v[112:127], v[180:183], v[212:215], v[112:127]
	v_mfma_f32_32x32x16_f16 v[96:111], v[180:183], v[220:223], v[96:111]
	v_mfma_f32_32x32x16_f16 v[80:95], v[188:191], v[212:215], v[80:95]
	v_mfma_f32_32x32x16_f16 v[64:79], v[188:191], v[220:223], v[64:79]
	v_mfma_f32_32x32x16_f16 v[48:63], v[196:199], v[212:215], v[48:63]
	v_mfma_f32_32x32x16_f16 v[32:47], v[196:199], v[220:223], v[32:47]
	v_mfma_f32_32x32x16_f16 v[16:31], v[204:207], v[212:215], v[16:31]
	v_mfma_f32_32x32x16_f16 v[0:15], v[204:207], v[220:223], v[0:15]
	s_waitcnt lgkmcnt(0)
	v_mfma_f32_32x32x16_f16 v[112:127], v[184:187], v[216:219], v[112:127]
	v_mfma_f32_32x32x16_f16 v[96:111], v[184:187], v[224:227], v[96:111]
	v_mfma_f32_32x32x16_f16 v[80:95], v[192:195], v[216:219], v[80:95]
	v_mfma_f32_32x32x16_f16 v[64:79], v[192:195], v[224:227], v[64:79]
	v_mfma_f32_32x32x16_f16 v[48:63], v[200:203], v[216:219], v[48:63]
	v_mfma_f32_32x32x16_f16 v[32:47], v[200:203], v[224:227], v[32:47]
	v_mfma_f32_32x32x16_f16 v[16:31], v[208:211], v[216:219], v[16:31]
	v_mfma_f32_32x32x16_f16 v[0:15], v[208:211], v[224:227], v[0:15]
	s_setprio 0
	v_ashrrev_i32_e32 v130, 1, v169
	v_lshlrev_b32_e32 v131, 6, v169
	v_mul_lo_u32 v129, v130, s9
	v_and_b32_e32 v131, 64, v131
	v_lshl_add_u32 v129, v131, 2, v129
	v_or_b32_e32 v132, s3, v131
	v_lshlrev_b32_e32 v131, 8, v167
	v_lshl_or_b32 v131, v168, 2, v131
	v_ashrrev_i32_e32 v132, 5, v132
	v_ashrrev_i32_e32 v128, 7, v169
	v_add_u32_e32 v130, s2, v130
	v_mad_u32_u24 v131, v166, s10, v131
	v_or_b32_e32 v133, 1, v132
	s_mov_b32 s15, 0
	s_mov_b64 s[2:3], -1
	s_branch .LBB0_981
